# v19: sample conformer-conv unit: all 30 state-row + 4 new-row loads issued up front (was a load/wait/store chain of ~15 exposed latencies), cutting the mixers-phase straggler waves
# speedup vs baseline: 1.0217x; 1.0217x over previous
; __device__ __forceinline__ float bf2f(bf16 b) { return __uint_as_float(((unsigned)b) << 16); }
; __device__ __forceinline__ float sigm(float x) { return __builtin_amdgcn_rcpf(1.f + __builtin_amdgcn_exp2f(-1.44269504f * x)); }
; template <bool SAMPLE> ...
;     const int c = h * 64 + lane;
;     const size_t rowbase = SAMPLE ? (size_t)MP + (size_t)seq * ST : (size_t)seq * SEQ;
;     const bf16* zc = Z + rowbase * ZP + c;
;     bf16* oc = CAT + rowbase * DP + 256 + c;
;     const int T = SAMPLE ? ST : SEQ;
;     const bool last = (t0 + nrows == T);
;     const int nin = nrows + 30;
; #pragma unroll
;     for (int r = 0; r < nin; ++r) { const int s = t0 - 30 + r; float gs = 0.f;
;         if (s >= 0) { const unsigned off = (unsigned)s * ZP; const float p = bf2f(zc[off + 256]), gt = bf2f(zc[off + 512]); gs = p * sigm(gt); }
;         else if (SAMPLE) gs = state[((size_t)seq * 30 + 30 + s) * GW + c];
;         if (last && s >= T - 30) newc[((size_t)seq * 30 + (s - (T - 30))) * GW + c] = gs;
;         gL[r * 64 + lane] = gs; }
.LBB0_138:
	s_and_b64 vcc, exec, s[4:5]
	s_cbranch_vccz .LBB0_140
	s_lshr_b32 s2, s6, 4
	v_mul_u32_u24_e32 v128, s2, v172
	s_lshl_b32 s2, s2, 6
	s_bitset1_b32 s2, 14
	s_waitcnt vmcnt(0)
	v_lshl_add_u64 v[0:1], s[62:63], 0, v[128:129]
	v_mul_hi_i32_i24_e32 v3, s2, v173
	v_mul_i32_i24_e32 v2, s2, v173
	v_lshl_add_u64 v[2:3], v[0:1], 0, v[2:3]
	v_mad_u64_u32 v[0:1], s[4:5], s2, v179, v[2:3]
	s_lshl_b32 s2, s6, 2
	s_bitset1_b32 s2, 14
	v_lshl_add_u32 v4, s7, 6, v124
	v_mad_u64_u32 v[6:7], s[4:5], s2, v175, v[2:3]
	v_ashrrev_i32_e32 v5, 31, v4
	v_readlane_b32 s4, v252, 20
	v_lshlrev_b64 v[2:3], 1, v[4:5]
	v_lshlrev_b64 v[4:5], 2, v[4:5]
	v_readlane_b32 s5, v252, 21
	v_lshl_add_u32 v12, v124, 2, s69
	v_lshl_add_u64 v[6:7], v[6:7], 0, v[2:3]
	v_lshl_add_u64 v[8:9], s[4:5], 0, v[4:5]
	v_readlane_b32 s4, v252, 22
	v_readlane_b32 s5, v252, 23
	s_lshl_b32 s84, s2, 11
	v_lshl_add_u64 v[0:1], v[0:1], 0, s[84:85]
	v_lshl_add_u64 v[14:15], s[4:5], 0, v[4:5]
	v_mad_u64_u32 v[10:11], s[4:5], s6, v180, v[8:9]
	v_lshl_add_u64 v[0:1], v[0:1], 0, v[2:3]
	v_mad_u64_u32 v[8:9], s[4:5], s6, v180, v[14:15]
	s_mov_b64 s[4:5], 0x48200
	v_lshl_add_u64 v[2:3], v[0:1], 0, s[4:5]
	global_load_dword v190, v[10:11], off
	global_load_dword v191, v[10:11], off offset:1024
	global_load_dword v192, v[10:11], off offset:2048
	global_load_dword v193, v[10:11], off offset:3072
	v_add_co_u32_e32 v232, vcc, 0x2000, v10
	s_nop 1
	v_addc_co_u32_e32 v233, vcc, 0, v11, vcc
	global_load_dword v194, v[232:233], off offset:-4096
	global_load_dword v195, v[232:233], off offset:-3072
	global_load_dword v196, v[232:233], off offset:-2048
	global_load_dword v197, v[232:233], off offset:-1024
	global_load_dword v198, v[232:233], off
	global_load_dword v199, v[232:233], off offset:1024
	global_load_dword v200, v[232:233], off offset:2048
	global_load_dword v201, v[232:233], off offset:3072
	v_add_co_u32_e32 v232, vcc, 0x4000, v10
	s_nop 1
	v_addc_co_u32_e32 v233, vcc, 0, v11, vcc
	global_load_dword v202, v[232:233], off offset:-4096
	global_load_dword v203, v[232:233], off offset:-3072
	global_load_dword v204, v[232:233], off offset:-2048
	global_load_dword v205, v[232:233], off offset:-1024
	global_load_dword v206, v[232:233], off
	global_load_dword v207, v[232:233], off offset:1024
	global_load_dword v208, v[232:233], off offset:2048
	global_load_dword v209, v[232:233], off offset:3072
	v_add_co_u32_e32 v232, vcc, 0x6000, v10
	s_nop 1
	v_addc_co_u32_e32 v233, vcc, 0, v11, vcc
	global_load_dword v210, v[232:233], off offset:-4096
	global_load_dword v211, v[232:233], off offset:-3072
	global_load_dword v212, v[232:233], off offset:-2048
	global_load_dword v213, v[232:233], off offset:-1024
	global_load_dword v214, v[232:233], off
	global_load_dword v215, v[232:233], off offset:1024
	global_load_dword v216, v[232:233], off offset:2048
	global_load_dword v217, v[232:233], off offset:3072
	v_add_co_u32_e32 v232, vcc, 0x8000, v10
	s_nop 1
	v_addc_co_u32_e32 v233, vcc, 0, v11, vcc
	global_load_dword v218, v[232:233], off offset:-4096
	global_load_dword v219, v[232:233], off offset:-3072
	global_load_ushort v220, v[6:7], off offset:512
	global_load_ushort v221, v[6:7], off offset:1024
	v_add_co_u32_e32 v232, vcc, 0x1000, v6
	s_nop 1
	v_addc_co_u32_e32 v233, vcc, 0, v7, vcc
	global_load_ushort v222, v[232:233], off offset:640
	global_load_ushort v223, v[232:233], off offset:1152
	v_add_co_u32_e32 v232, vcc, 0x2000, v6
	s_nop 1
	v_addc_co_u32_e32 v233, vcc, 0, v7, vcc
	global_load_ushort v224, v[232:233], off offset:768
	global_load_ushort v225, v[232:233], off offset:1280
	v_add_co_u32_e32 v232, vcc, 0x3000, v6
	s_nop 1
	v_addc_co_u32_e32 v233, vcc, 0, v7, vcc
	global_load_ushort v226, v[232:233], off offset:896
	global_load_ushort v227, v[232:233], off offset:1408
	s_waitcnt vmcnt(0)
	v_lshlrev_b32_e32 v220, 16, v220
	v_lshlrev_b32_e32 v221, 16, v221
	v_mul_f32_e32 v221, 0xbfb8aa3b, v221
	v_exp_f32_e32 v221, v221
	s_nop 0
	v_add_f32_e32 v221, 1.0, v221
	v_rcp_f32_e32 v221, v221
	s_nop 0
	v_mul_f32_e32 v228, v221, v220
	v_lshlrev_b32_e32 v222, 16, v222
	v_lshlrev_b32_e32 v223, 16, v223
	v_mul_f32_e32 v223, 0xbfb8aa3b, v223
	v_exp_f32_e32 v223, v223
	s_nop 0
	v_add_f32_e32 v223, 1.0, v223
	v_rcp_f32_e32 v223, v223
	s_nop 0
	v_mul_f32_e32 v229, v223, v222
	v_lshlrev_b32_e32 v224, 16, v224
	v_lshlrev_b32_e32 v225, 16, v225
	v_mul_f32_e32 v225, 0xbfb8aa3b, v225
	v_exp_f32_e32 v225, v225
	s_nop 0
	v_add_f32_e32 v225, 1.0, v225
	v_rcp_f32_e32 v225, v225
	s_nop 0
	v_mul_f32_e32 v230, v225, v224
	v_lshlrev_b32_e32 v226, 16, v226
	v_lshlrev_b32_e32 v227, 16, v227
	v_mul_f32_e32 v227, 0xbfb8aa3b, v227
	v_exp_f32_e32 v227, v227
	s_nop 0
	v_add_f32_e32 v227, 1.0, v227
	v_rcp_f32_e32 v227, v227
	s_nop 0
	v_mul_f32_e32 v231, v227, v226
	ds_write2st64_b32 v12, v190, v191 offset1:1
	ds_write2st64_b32 v12, v192, v193 offset0:2 offset1:3
	ds_write2st64_b32 v12, v194, v195 offset0:4 offset1:5
	ds_write2st64_b32 v12, v196, v197 offset0:6 offset1:7
	ds_write2st64_b32 v12, v198, v199 offset0:8 offset1:9
	ds_write2st64_b32 v12, v200, v201 offset0:10 offset1:11
	ds_write2st64_b32 v12, v202, v203 offset0:12 offset1:13
	ds_write2st64_b32 v12, v204, v205 offset0:14 offset1:15
	ds_write2st64_b32 v12, v206, v207 offset0:16 offset1:17
	ds_write2st64_b32 v12, v208, v209 offset0:18 offset1:19
	ds_write2st64_b32 v12, v210, v211 offset0:20 offset1:21
	ds_write2st64_b32 v12, v212, v213 offset0:22 offset1:23
	ds_write2st64_b32 v12, v214, v215 offset0:24 offset1:25
	ds_write2st64_b32 v12, v216, v217 offset0:26 offset1:27
	ds_write2st64_b32 v12, v218, v219 offset0:28 offset1:29
	ds_write2st64_b32 v12, v228, v229 offset0:30 offset1:31
; #define LDS_WAIT() asm volatile("s_waitcnt lgkmcnt(0)" ::: "memory")
; template <bool SAMPLE> ...
;     ...
;         if (last && s >= T - 30) newc[((size_t)seq * 30 + (s - (T - 30))) * GW + c] = gs;
;         gL[r * 64 + lane] = gs; }
;     LDS_WAIT();
;     float wk[31];
; #pragma unroll
;     for (int k = 0; k < 31; ++k) wk[k] = cw[k * GW + c];
;     const float bias = cb[c], gg = lg[c], bb = lb[c];
; #pragma unroll 1
;     for (int tq = 0; tq < nrows; tq += 4) {
;         float acc[4] = {bias, bias, bias, bias};
; #pragma unroll
;         for (int r = 0; r < 34; ++r) { const float gv = gL[(tq + r) * 64 + lane];
	ds_write2st64_b32 v12, v230, v231 offset0:32 offset1:33
	global_store_dword v[8:9], v194, off
	global_store_dword v[8:9], v195, off offset:1024
	global_store_dword v[8:9], v196, off offset:2048
	global_store_dword v[8:9], v197, off offset:3072
	v_add_co_u32_e32 v232, vcc, 0x2000, v8
	s_nop 1
	v_addc_co_u32_e32 v233, vcc, 0, v9, vcc
	global_store_dword v[232:233], v198, off offset:-4096
	global_store_dword v[232:233], v199, off offset:-3072
	global_store_dword v[232:233], v200, off offset:-2048
	global_store_dword v[232:233], v201, off offset:-1024
	global_store_dword v[232:233], v202, off
	global_store_dword v[232:233], v203, off offset:1024
	global_store_dword v[232:233], v204, off offset:2048
	global_store_dword v[232:233], v205, off offset:3072
	v_add_co_u32_e32 v232, vcc, 0x4000, v8
	s_nop 1
	v_addc_co_u32_e32 v233, vcc, 0, v9, vcc
	global_store_dword v[232:233], v206, off offset:-4096
	global_store_dword v[232:233], v207, off offset:-3072
	global_store_dword v[232:233], v208, off offset:-2048
	global_store_dword v[232:233], v209, off offset:-1024
	global_store_dword v[232:233], v210, off
	global_store_dword v[232:233], v211, off offset:1024
	global_store_dword v[232:233], v212, off offset:2048
	global_store_dword v[232:233], v213, off offset:3072
	v_add_co_u32_e32 v232, vcc, 0x6000, v8
	s_nop 1
	v_addc_co_u32_e32 v233, vcc, 0, v9, vcc
	global_store_dword v[232:233], v214, off offset:-4096
	global_store_dword v[232:233], v215, off offset:-3072
	global_store_dword v[232:233], v216, off offset:-2048
	global_store_dword v[232:233], v217, off offset:-1024
	global_store_dword v[232:233], v218, off
	global_store_dword v[232:233], v219, off offset:1024
	global_store_dword v[232:233], v228, off offset:2048
	global_store_dword v[232:233], v229, off offset:3072
	v_add_co_u32_e32 v232, vcc, 0x8000, v8
	s_nop 1
	v_addc_co_u32_e32 v233, vcc, 0, v9, vcc
	global_store_dword v[232:233], v230, off offset:-4096
	global_store_dword v[232:233], v231, off offset:-3072
	v_lshl_add_u64 v[6:7], s[52:53], 0, v[4:5]
	v_add_co_u32_e32 v8, vcc, s30, v6
	s_waitcnt lgkmcnt(0)
	global_load_dword v16, v[6:7], off
	global_load_dword v15, v[6:7], off offset:1024
	global_load_dword v14, v[6:7], off offset:2048
	global_load_dword v13, v[6:7], off offset:3072
	v_addc_co_u32_e32 v9, vcc, 0, v7, vcc
	v_add_co_u32_e32 v10, vcc, s21, v6
	s_nop 1
	v_addc_co_u32_e32 v11, vcc, 0, v7, vcc
	global_load_dword v24, v[10:11], off offset:-4096
	global_load_dword v23, v[8:9], off offset:1024
	global_load_dword v22, v[8:9], off offset:2048
	global_load_dword v21, v[8:9], off offset:3072
	global_load_dword v20, v[10:11], off
	global_load_dword v19, v[10:11], off offset:1024
	global_load_dword v18, v[10:11], off offset:2048
	global_load_dword v17, v[10:11], off offset:3072
	v_add_co_u32_e32 v8, vcc, s31, v6
	s_nop 1
	v_addc_co_u32_e32 v9, vcc, 0, v7, vcc
	v_add_co_u32_e32 v10, vcc, s28, v6
	s_nop 1
	v_addc_co_u32_e32 v11, vcc, 0, v7, vcc
	global_load_dword v25, v[10:11], off offset:-4096
	global_load_dword v41, v[8:9], off offset:1024
	global_load_dword v40, v[8:9], off offset:2048
	global_load_dword v39, v[8:9], off offset:3072
	global_load_dword v37, v[10:11], off
	global_load_dword v35, v[10:11], off offset:1024
	global_load_dword v33, v[10:11], off offset:2048
	global_load_dword v31, v[10:11], off offset:3072
	v_add_co_u32_e32 v8, vcc, s36, v6
	s_nop 1
	v_addc_co_u32_e32 v9, vcc, 0, v7, vcc
	v_add_co_u32_e32 v10, vcc, s29, v6
	s_nop 1
	v_addc_co_u32_e32 v11, vcc, 0, v7, vcc
	global_load_dword v38, v[10:11], off offset:-4096
	global_load_dword v36, v[8:9], off offset:1024
	global_load_dword v34, v[8:9], off offset:2048
	global_load_dword v32, v[8:9], off offset:3072
	global_load_dword v30, v[10:11], off
	global_load_dword v29, v[10:11], off offset:1024
	global_load_dword v27, v[10:11], off offset:2048
	global_load_dword v26, v[10:11], off offset:3072
	v_add_co_u32_e32 v8, vcc, s37, v6
	s_nop 1
	v_addc_co_u32_e32 v9, vcc, 0, v7, vcc
	global_load_dword v28, v[8:9], off
	global_load_dword v6, v[8:9], off offset:1024
	global_load_dword v7, v[8:9], off offset:2048
	v_lshl_add_u64 v[8:9], s[54:55], 0, v[4:5]
	global_load_dword v11, v[8:9], off
	v_lshl_add_u64 v[8:9], s[26:27], 0, v[4:5]
	v_lshl_add_u64 v[4:5], s[44:45], 0, v[4:5]
	global_load_dword v76, v[4:5], off
	global_load_dword v10, v[8:9], off
	ds_read2st64_b32 v[8:9], v12 offset1:1
	ds_read2st64_b32 v[42:43], v12 offset0:2 offset1:3
	ds_read2st64_b32 v[44:45], v12 offset0:4 offset1:5
	ds_read2st64_b32 v[46:47], v12 offset0:6 offset1:7
	ds_read2st64_b32 v[48:49], v12 offset0:8 offset1:9
	ds_read2st64_b32 v[50:51], v12 offset0:10 offset1:11
	ds_read2st64_b32 v[52:53], v12 offset0:12 offset1:13
	ds_read2st64_b32 v[54:55], v12 offset0:14 offset1:15
	ds_read2st64_b32 v[56:57], v12 offset0:16 offset1:17
	ds_read2st64_b32 v[58:59], v12 offset0:18 offset1:19
	ds_read2st64_b32 v[60:61], v12 offset0:20 offset1:21
	ds_read2st64_b32 v[62:63], v12 offset0:22 offset1:23
	ds_read2st64_b32 v[64:65], v12 offset0:24 offset1:25
	ds_read2st64_b32 v[66:67], v12 offset0:26 offset1:27
	ds_read2st64_b32 v[68:69], v12 offset0:28 offset1:29
	ds_read2st64_b32 v[70:71], v12 offset0:30 offset1:31
	ds_read2st64_b32 v[72:73], v12 offset0:32 offset1:33
	s_waitcnt lgkmcnt(2)
	v_mov_b32_e32 v74, v69
	s_waitcnt lgkmcnt(1)
	v_mov_b32_e32 v75, v70
	s_waitcnt vmcnt(3) lgkmcnt(0)
	v_pk_mul_f32 v[4:5], v[6:7], v[72:73]
	v_pk_mul_f32 v[74:75], v[6:7], v[74:75]
	s_waitcnt vmcnt(1)
; template <bool SAMPLE> ...
;     ...
;     for (int tq = 0; tq < nrows; tq += 4) {
;         float acc[4] = {bias, bias, bias, bias};
; #pragma unroll
;         for (int r = 0; r < 34; ++r) { const float gv = gL[(tq + r) * 64 + lane];
; #pragma unroll
;             for (int q = 0; q < 4; ++q) { const int k = r - q; if (k >= 0 && k <= 30) acc[q] += wk[k] * gv; } }
; #pragma unroll
;         for (int q = 0; q < 4; ++q) { const float cv = acc[q];
;             const float mean = wave_sum(cv) * (1.f / 64.f); const float d = cv - mean;
;             const float var = wave_sum(d * d) * (1.f / 64.f);
;             const float y = d * rsqrtf(var + EPS) * gg + bb;
	v_fma_f32 v12, v16, v43, v76
	v_fmac_f32_e32 v12, v15, v44
	v_fmac_f32_e32 v12, v14, v45
	v_fmac_f32_e32 v12, v13, v46
	v_fmac_f32_e32 v12, v24, v47
	v_fmac_f32_e32 v12, v23, v48
	v_fmac_f32_e32 v12, v22, v49
	v_fmac_f32_e32 v12, v21, v50
	v_fmac_f32_e32 v12, v20, v51
	v_fmac_f32_e32 v12, v19, v52
	v_fmac_f32_e32 v12, v18, v53
	v_fmac_f32_e32 v12, v17, v54
	v_fmac_f32_e32 v12, v25, v55
	v_fmac_f32_e32 v12, v41, v56
	v_fmac_f32_e32 v12, v40, v57
	v_fmac_f32_e32 v12, v39, v58
	v_fmac_f32_e32 v12, v37, v59
	v_fmac_f32_e32 v12, v35, v60
	v_fmac_f32_e32 v12, v33, v61
	v_fmac_f32_e32 v12, v31, v62
	v_fmac_f32_e32 v12, v38, v63
	v_fmac_f32_e32 v12, v36, v64
	v_fmac_f32_e32 v12, v34, v65
	v_fmac_f32_e32 v12, v32, v66
	v_fmac_f32_e32 v12, v30, v67
	v_fmac_f32_e32 v12, v29, v68
	v_fmac_f32_e32 v12, v27, v69
	v_fmac_f32_e32 v12, v26, v70
	v_fmac_f32_e32 v12, v28, v71
	v_add_f32_e32 v4, v12, v4
	v_fma_f32 v12, v16, v9, v76
	v_fmac_f32_e32 v12, v15, v42
	v_add_f32_e32 v4, v4, v5
	v_fma_f32 v5, v16, v8, v76
	v_fmac_f32_e32 v12, v14, v43
	v_fmac_f32_e32 v5, v15, v9
	v_fmac_f32_e32 v12, v13, v44
	v_fmac_f32_e32 v76, v16, v42
	v_fmac_f32_e32 v5, v14, v42
	v_fmac_f32_e32 v12, v24, v45
	v_fmac_f32_e32 v76, v15, v43
	v_fmac_f32_e32 v5, v13, v43
	v_fmac_f32_e32 v12, v23, v46
	v_fmac_f32_e32 v76, v14, v44
	v_fmac_f32_e32 v5, v24, v44
	v_fmac_f32_e32 v12, v22, v47
	v_fmac_f32_e32 v76, v13, v45
	v_fmac_f32_e32 v5, v23, v45
	v_fmac_f32_e32 v12, v21, v48
	v_fmac_f32_e32 v76, v24, v46
	v_fmac_f32_e32 v5, v22, v46
	v_fmac_f32_e32 v12, v20, v49
	v_fmac_f32_e32 v76, v23, v47
	v_fmac_f32_e32 v5, v21, v47
	v_fmac_f32_e32 v12, v19, v50
	v_fmac_f32_e32 v76, v22, v48
	v_fmac_f32_e32 v5, v20, v48
	v_fmac_f32_e32 v12, v18, v51
	v_fmac_f32_e32 v76, v21, v49
	v_fmac_f32_e32 v5, v19, v49
	v_fmac_f32_e32 v12, v17, v52
	v_fmac_f32_e32 v76, v20, v50
	v_fmac_f32_e32 v5, v18, v50
	v_fmac_f32_e32 v12, v25, v53
	v_fmac_f32_e32 v76, v19, v51
	v_fmac_f32_e32 v5, v17, v51
	v_fmac_f32_e32 v12, v41, v54
	v_fmac_f32_e32 v76, v18, v52
	v_fmac_f32_e32 v5, v25, v52
	v_fmac_f32_e32 v12, v40, v55
	v_fmac_f32_e32 v76, v17, v53
	v_fmac_f32_e32 v5, v41, v53
	v_fmac_f32_e32 v12, v39, v56
	v_fmac_f32_e32 v76, v25, v54
	v_fmac_f32_e32 v5, v40, v54
	v_fmac_f32_e32 v12, v37, v57
	v_fmac_f32_e32 v76, v41, v55
	v_fmac_f32_e32 v5, v39, v55
	v_fmac_f32_e32 v12, v35, v58
	v_fmac_f32_e32 v76, v40, v56
	v_fmac_f32_e32 v5, v37, v56
	v_fmac_f32_e32 v12, v33, v59
	v_fmac_f32_e32 v76, v39, v57
	v_fmac_f32_e32 v5, v35, v57
	v_fmac_f32_e32 v12, v31, v60
	v_fmac_f32_e32 v76, v37, v58
	v_fmac_f32_e32 v5, v33, v58
	v_fmac_f32_e32 v12, v38, v61
	v_fmac_f32_e32 v76, v35, v59
	v_fmac_f32_e32 v5, v31, v59
	v_fmac_f32_e32 v12, v36, v62
	v_fmac_f32_e32 v76, v33, v60
	v_fmac_f32_e32 v5, v38, v60
	v_fmac_f32_e32 v12, v34, v63
	v_fmac_f32_e32 v76, v31, v61
	v_fmac_f32_e32 v5, v36, v61
	v_fmac_f32_e32 v12, v32, v64
	v_fmac_f32_e32 v76, v38, v62
	v_fmac_f32_e32 v5, v34, v62
	v_fmac_f32_e32 v12, v30, v65
	v_fmac_f32_e32 v76, v36, v63
	v_fmac_f32_e32 v5, v32, v63
	v_fmac_f32_e32 v12, v29, v66
	v_fmac_f32_e32 v76, v34, v64
	v_fmac_f32_e32 v5, v30, v64
	v_fmac_f32_e32 v12, v27, v67
	v_fmac_f32_e32 v76, v32, v65
	v_fmac_f32_e32 v5, v29, v65
	v_fmac_f32_e32 v12, v26, v68
	v_fmac_f32_e32 v76, v30, v66
	v_fmac_f32_e32 v5, v27, v66
	v_fmac_f32_e32 v12, v28, v69
	v_pk_mul_f32 v[8:9], v[6:7], v[70:71]
	v_fmac_f32_e32 v76, v29, v67
	v_fmac_f32_e32 v5, v26, v67
	v_add_f32_e32 v8, v12, v8
	v_fmac_f32_e32 v76, v27, v68
	v_fmac_f32_e32 v5, v28, v68
	v_add_f32_e32 v12, v8, v9
	v_fmac_f32_e32 v76, v26, v69
	v_mov_b32_e32 v8, v71
	v_mov_b32_e32 v9, v72
	v_add_f32_e32 v5, v5, v74
	v_fmac_f32_e32 v76, v28, v70
	v_pk_mul_f32 v[6:7], v[6:7], v[8:9]
	v_add_f32_e32 v5, v5, v75
	v_add_f32_e32 v6, v76, v6
	v_add_f32_e32 v8, v6, v7
	v_mov_b32_e32 v7, v129
	v_add_f32_dpp v6, v5, v5 quad_perm:[1,0,3,2] row_mask:0xf bank_mask:0xf bound_ctrl:1
	s_nop 1
	v_add_f32_dpp v6, v6, v6 quad_perm:[2,3,0,1] row_mask:0xf bank_mask:0xf bound_ctrl:1
	s_nop 1
	v_add_f32_dpp v6, v6, v6 row_half_mirror row_mask:0xf bank_mask:0xf bound_ctrl:1
	s_nop 1
	v_add_f32_dpp v6, v6, v6 row_mirror row_mask:0xf bank_mask:0xf bound_ctrl:1
	s_nop 1
	v_mov_b32_dpp v7, v6 row_bcast:15 row_mask:0xa bank_mask:0xf
	v_add_f32_e32 v6, v6, v7
	v_mov_b32_e32 v7, v129
	s_nop 1
	v_mov_b32_dpp v7, v6 row_bcast:31 row_mask:0xc bank_mask:0xf
	v_add_f32_e32 v6, v6, v7
	v_mov_b32_e32 v7, v129
	v_readlane_b32 s2, v6, 63
	s_nop 1
	v_fmac_f32_e32 v5, s2, v176
	v_mul_f32_e32 v6, v5, v5
	s_nop 1
	v_mov_b32_dpp v7, v6 quad_perm:[1,0,3,2] row_mask:0xf bank_mask:0xf
	v_fmac_f32_e32 v7, v5, v5
	s_nop 1
	v_add_f32_dpp v6, v7, v7 quad_perm:[2,3,0,1] row_mask:0xf bank_mask:0xf bound_ctrl:1
	v_mov_b32_e32 v7, v129
	s_nop 0
	v_add_f32_dpp v6, v6, v6 row_half_mirror row_mask:0xf bank_mask:0xf bound_ctrl:1
	s_nop 1
	v_add_f32_dpp v6, v6, v6 row_mirror row_mask:0xf bank_mask:0xf bound_ctrl:1
	s_nop 1
	v_mov_b32_dpp v7, v6 row_bcast:15 row_mask:0xa bank_mask:0xf
	v_add_f32_e32 v6, v6, v7
	v_mov_b32_e32 v7, v129
	s_nop 1
	v_mov_b32_dpp v7, v6 row_bcast:31 row_mask:0xc bank_mask:0xf
	v_add_f32_e32 v6, v6, v7
	s_nop 0
	v_readlane_b32 s2, v6, 63
	s_nop 1
	v_fma_f32 v6, s2, v177, v168
	v_cmp_gt_f32_e32 vcc, s79, v6
	v_mul_f32_e32 v7, 0x4b800000, v6
	s_mov_b32 s2, 0x48000
	v_cndmask_b32_e32 v6, v6, v7, vcc
	v_rsq_f32_e32 v6, v6
	s_nop 0
	v_mul_f32_e32 v7, 0x45800000, v6
	v_cndmask_b32_e32 v6, v6, v7, vcc
	v_mul_f32_e32 v5, v5, v6
	s_waitcnt vmcnt(0)
; __device__ __forceinline__ unsigned f2bf(float f) { unsigned u = __float_as_uint(f); return (u + 0x7fffu + ((u >> 16) & 1u)) >> 16; }
; __device__ __forceinline__ float sigm(float x) { return __builtin_amdgcn_rcpf(1.f + __builtin_amdgcn_exp2f(-1.44269504f * x)); }
; template <bool SAMPLE> ...
;     ...
;         for (int q = 0; q < 4; ++q) { const float cv = acc[q];
;             const float mean = wave_sum(cv) * (1.f / 64.f); const float d = cv - mean;
;             const float var = wave_sum(d * d) * (1.f / 64.f);
;             const float y = d * rsqrtf(var + EPS) * gg + bb;
;             oc[(unsigned)(t0 + tq + q) * DP] = (bf16)f2bf(y * sigm(y)); }
	v_fma_f32 v5, v11, v5, v10
	v_mul_f32_e32 v6, 0xbfb8aa3b, v5
	v_exp_f32_e32 v6, v6
	s_nop 0
	v_add_f32_e32 v6, 1.0, v6
	v_rcp_f32_e32 v6, v6
	s_nop 0
	v_mul_f32_e32 v5, v5, v6
	v_bfe_u32 v6, v5, 16, 1
	v_add3_u32 v5, v5, v6, s90
	v_add_co_u32_e32 v6, vcc, s2, v0
	s_nop 1
	v_addc_co_u32_e32 v7, vcc, 0, v1, vcc
	global_store_short_d16_hi v[6:7], v5, off offset:512
	v_add_f32_dpp v5, v12, v12 quad_perm:[1,0,3,2] row_mask:0xf bank_mask:0xf bound_ctrl:1
	v_mov_b32_e32 v6, v129
	s_nop 0
	v_add_f32_dpp v5, v5, v5 quad_perm:[2,3,0,1] row_mask:0xf bank_mask:0xf bound_ctrl:1
	s_nop 1
	v_add_f32_dpp v5, v5, v5 row_half_mirror row_mask:0xf bank_mask:0xf bound_ctrl:1
	s_nop 1
	v_add_f32_dpp v5, v5, v5 row_mirror row_mask:0xf bank_mask:0xf bound_ctrl:1
	s_nop 1
	v_mov_b32_dpp v6, v5 row_bcast:15 row_mask:0xa bank_mask:0xf
	v_add_f32_e32 v5, v5, v6
	v_mov_b32_e32 v6, v129
	s_nop 1
	v_mov_b32_dpp v6, v5 row_bcast:31 row_mask:0xc bank_mask:0xf
	v_add_f32_e32 v5, v5, v6
	v_mov_b32_e32 v6, v129
	v_readlane_b32 s2, v5, 63
	s_nop 1
	v_fmac_f32_e32 v12, s2, v176
	v_mul_f32_e32 v5, v12, v12
	s_nop 1
	v_mov_b32_dpp v6, v5 quad_perm:[1,0,3,2] row_mask:0xf bank_mask:0xf
	v_fmac_f32_e32 v6, v12, v12
	s_nop 1
	v_add_f32_dpp v5, v6, v6 quad_perm:[2,3,0,1] row_mask:0xf bank_mask:0xf bound_ctrl:1
	v_mov_b32_e32 v6, v129
	s_nop 0
	v_add_f32_dpp v5, v5, v5 row_half_mirror row_mask:0xf bank_mask:0xf bound_ctrl:1
	s_nop 1
	v_add_f32_dpp v5, v5, v5 row_mirror row_mask:0xf bank_mask:0xf bound_ctrl:1
	s_nop 1
	v_mov_b32_dpp v6, v5 row_bcast:15 row_mask:0xa bank_mask:0xf
	v_add_f32_e32 v5, v5, v6
	v_mov_b32_e32 v6, v129
	s_nop 1
	v_mov_b32_dpp v6, v5 row_bcast:31 row_mask:0xc bank_mask:0xf
	v_add_f32_e32 v5, v5, v6
	s_nop 0
	v_readlane_b32 s2, v5, 63
	s_nop 1
	v_fma_f32 v5, s2, v177, v168
	v_cmp_gt_f32_e32 vcc, s79, v5
	v_mul_f32_e32 v6, 0x4b800000, v5
	s_nop 0
	v_cndmask_b32_e32 v5, v5, v6, vcc
	v_rsq_f32_e32 v5, v5
	s_nop 0
	v_mul_f32_e32 v6, 0x45800000, v5
	v_cndmask_b32_e32 v5, v5, v6, vcc
	v_mul_f32_e32 v5, v12, v5
	v_fma_f32 v5, v11, v5, v10
	v_mul_f32_e32 v6, 0xbfb8aa3b, v5
	v_exp_f32_e32 v6, v6
	s_nop 0
	v_add_f32_e32 v6, 1.0, v6
	v_rcp_f32_e32 v6, v6
	s_nop 0
	v_mul_f32_e32 v5, v5, v6
	v_bfe_u32 v6, v5, 16, 1
	v_add3_u32 v5, v5, v6, s90
	global_store_short_d16_hi v[2:3], v5, off offset:2048
	v_add_f32_dpp v2, v8, v8 quad_perm:[1,0,3,2] row_mask:0xf bank_mask:0xf bound_ctrl:1
	v_mov_b32_e32 v3, v129
	s_nop 0
	v_add_f32_dpp v2, v2, v2 quad_perm:[2,3,0,1] row_mask:0xf bank_mask:0xf bound_ctrl:1
	s_nop 1
	v_add_f32_dpp v2, v2, v2 row_half_mirror row_mask:0xf bank_mask:0xf bound_ctrl:1
	s_nop 1
	v_add_f32_dpp v2, v2, v2 row_mirror row_mask:0xf bank_mask:0xf bound_ctrl:1
	s_nop 1
	v_mov_b32_dpp v3, v2 row_bcast:15 row_mask:0xa bank_mask:0xf
	v_add_f32_e32 v2, v2, v3
	v_mov_b32_e32 v3, v129
	s_nop 1
	v_mov_b32_dpp v3, v2 row_bcast:31 row_mask:0xc bank_mask:0xf
	v_add_f32_e32 v2, v2, v3
	v_mov_b32_e32 v3, v129
	v_readlane_b32 s2, v2, 63
	s_nop 1
	v_fmac_f32_e32 v8, s2, v176
	v_mul_f32_e32 v2, v8, v8
	s_nop 1
	v_mov_b32_dpp v3, v2 quad_perm:[1,0,3,2] row_mask:0xf bank_mask:0xf
	v_fmac_f32_e32 v3, v8, v8
	s_nop 1
	v_add_f32_dpp v2, v3, v3 quad_perm:[2,3,0,1] row_mask:0xf bank_mask:0xf bound_ctrl:1
	v_mov_b32_e32 v3, v129
	s_nop 0
	v_add_f32_dpp v2, v2, v2 row_half_mirror row_mask:0xf bank_mask:0xf bound_ctrl:1
	s_nop 1
	v_add_f32_dpp v2, v2, v2 row_mirror row_mask:0xf bank_mask:0xf bound_ctrl:1
	s_nop 1
	v_mov_b32_dpp v3, v2 row_bcast:15 row_mask:0xa bank_mask:0xf
	v_add_f32_e32 v2, v2, v3
	v_mov_b32_e32 v3, v129
	s_nop 1
	v_mov_b32_dpp v3, v2 row_bcast:31 row_mask:0xc bank_mask:0xf
	v_add_f32_e32 v2, v2, v3
	s_nop 0
	v_readlane_b32 s2, v2, 63
	s_nop 1
	v_fma_f32 v2, s2, v177, v168
	v_cmp_gt_f32_e32 vcc, s79, v2
	v_mul_f32_e32 v3, 0x4b800000, v2
	s_mov_b32 s2, 0x49000
	v_cndmask_b32_e32 v2, v2, v3, vcc
	v_rsq_f32_e32 v2, v2
	s_nop 0
	v_mul_f32_e32 v3, 0x45800000, v2
	v_cndmask_b32_e32 v2, v2, v3, vcc
	v_mul_f32_e32 v2, v8, v2
	v_fma_f32 v2, v11, v2, v10
	v_mul_f32_e32 v3, 0xbfb8aa3b, v2
	v_exp_f32_e32 v3, v3
	v_add_co_u32_e32 v0, vcc, s2, v0
	v_add_f32_e32 v3, 1.0, v3
	v_rcp_f32_e32 v3, v3
	v_addc_co_u32_e32 v1, vcc, 0, v1, vcc
	v_mul_f32_e32 v2, v2, v3
	v_bfe_u32 v3, v2, 16, 1
	v_add3_u32 v2, v2, v3, s90
	global_store_short_d16_hi v[0:1], v2, off offset:512
	v_mov_b32_e32 v3, v129
	v_add_f32_dpp v2, v4, v4 quad_perm:[1,0,3,2] row_mask:0xf bank_mask:0xf bound_ctrl:1
	s_nop 1
	v_add_f32_dpp v2, v2, v2 quad_perm:[2,3,0,1] row_mask:0xf bank_mask:0xf bound_ctrl:1
	s_nop 1
	v_add_f32_dpp v2, v2, v2 row_half_mirror row_mask:0xf bank_mask:0xf bound_ctrl:1
	s_nop 1
	v_add_f32_dpp v2, v2, v2 row_mirror row_mask:0xf bank_mask:0xf bound_ctrl:1
	s_nop 1
	v_mov_b32_dpp v3, v2 row_bcast:15 row_mask:0xa bank_mask:0xf
	v_add_f32_e32 v2, v2, v3
	v_mov_b32_e32 v3, v129
	s_nop 1
	v_mov_b32_dpp v3, v2 row_bcast:31 row_mask:0xc bank_mask:0xf
	v_add_f32_e32 v2, v2, v3
	v_mov_b32_e32 v3, v129
	v_readlane_b32 s2, v2, 63
	s_nop 1
	v_fmac_f32_e32 v4, s2, v176
	v_mul_f32_e32 v2, v4, v4
	s_nop 1
	v_mov_b32_dpp v3, v2 quad_perm:[1,0,3,2] row_mask:0xf bank_mask:0xf
	v_fmac_f32_e32 v3, v4, v4
	s_nop 1
	v_add_f32_dpp v2, v3, v3 quad_perm:[2,3,0,1] row_mask:0xf bank_mask:0xf bound_ctrl:1
	v_mov_b32_e32 v3, v129
	s_nop 0
	v_add_f32_dpp v2, v2, v2 row_half_mirror row_mask:0xf bank_mask:0xf bound_ctrl:1
	s_nop 1
	v_add_f32_dpp v2, v2, v2 row_mirror row_mask:0xf bank_mask:0xf bound_ctrl:1
	s_nop 1
	v_mov_b32_dpp v3, v2 row_bcast:15 row_mask:0xa bank_mask:0xf
	v_add_f32_e32 v2, v2, v3
	v_mov_b32_e32 v3, v129
	s_nop 1
	v_mov_b32_dpp v3, v2 row_bcast:31 row_mask:0xc bank_mask:0xf
	v_add_f32_e32 v2, v2, v3
	s_nop 0
	v_readlane_b32 s2, v2, 63
	s_nop 1
	v_fma_f32 v2, s2, v177, v168
	v_cmp_gt_f32_e32 vcc, s79, v2
	v_mul_f32_e32 v3, 0x4b800000, v2
	s_nop 0
	v_cndmask_b32_e32 v2, v2, v3, vcc
	v_rsq_f32_e32 v2, v2
	s_nop 0
	v_mul_f32_e32 v3, 0x45800000, v2
	v_cndmask_b32_e32 v2, v2, v3, vcc
	v_mul_f32_e32 v2, v4, v2
	v_fmac_f32_e32 v10, v11, v2
	v_mul_f32_e32 v2, 0xbfb8aa3b, v10
	v_exp_f32_e32 v2, v2
	s_nop 0
	v_add_f32_e32 v2, 1.0, v2
	v_rcp_f32_e32 v2, v2
	s_nop 0
	v_mul_f32_e32 v2, v10, v2
	v_bfe_u32 v3, v2, 16, 1
	v_add3_u32 v2, v2, v3, s90
	global_store_short_d16_hi v[0:1], v2, off offset:2560
	s_waitcnt lgkmcnt(0)
